# GA loop: v_max3 trees, softmax reference folded into QK accumulator init, permlane-swap cross-lane max, K reads at tile top, LDS tile writes issued at PV start
# speedup vs baseline: 1.0366x; 1.0199x over previous
.LBB0_1273:
	s_andn2_b64 vcc, exec, s[0:1]
	s_cbranch_vccnz .LBB0_1287
	s_lshl_b32 s0, s22, 1
	s_addk_i32 s0, 0xfeb0
	v_mov_b32_e32 v20, v201
	v_add_u32_e32 v8, s0, v149
	v_lshlrev_b32_e32 v0, 6, v8
	v_lshrrev_b32_e32 v6, 1, v20
	v_and_b32_e32 v2, 32, v6
	s_movk_i32 s0, 0xfc0
	v_ashrrev_i32_e32 v106, 7, v8
	v_bfe_u32 v5, v8, 6, 1
	v_and_or_b32 v0, v0, s0, v2
	v_mov_b64_e32 v[2:3], s[42:43]
	s_mov_b32 s0, 0x220000
	v_mad_i64_i32 v[2:3], s[0:1], v106, s0, v[2:3]
	v_lshlrev_b32_e32 v4, 7, v5
	v_and_or_b32 v110, v6, 64, v4
	v_mov_b64_e32 v[6:7], s[58:59]
	s_mov_b32 s0, 0x110000
	v_add_u32_e32 v108, 0x100, v0
	v_lshlrev_b32_e32 v0, 1, v110
	v_mad_i64_i32 v[6:7], s[0:1], v106, s0, v[6:7]
	v_and_b32_e32 v107, 15, v20
	v_bfe_u32 v21, v20, 4, 2
	v_lshl_add_u64 v[2:3], v[2:3], 0, v[0:1]
	v_lshlrev_b32_e32 v0, 6, v5
	v_mov_b32_e32 v5, v1
	s_movk_i32 s0, 0xff80
	v_lshl_add_u64 v[4:5], v[6:7], 0, v[4:5]
	v_and_or_b32 v6, v8, s0, v0
	v_or_b32_e32 v7, v108, v107
	v_lshlrev_b32_e32 v0, 4, v21
	v_lshl_add_u64 v[2:3], v[2:3], 0, v[0:1]
	v_lshlrev_b32_e32 v0, 9, v7
	v_lshl_add_u64 v[2:3], v[2:3], 0, v[0:1]
	s_movk_i32 s0, 0x2000
	global_load_dwordx4 v[46:49], v[2:3], off
	global_load_dwordx4 v[42:45], v[2:3], off offset:64
	v_add_co_u32_e32 v2, vcc, s0, v2
	v_and_b32_e32 v22, 7, v20
	s_nop 0
	v_addc_co_u32_e32 v3, vcc, 0, v3, vcc
	global_load_dwordx4 v[50:53], v[2:3], off
	global_load_dwordx4 v[54:57], v[2:3], off offset:64
	v_mov_b64_e32 v[2:3], s[44:45]
	v_bfe_u32 v126, v20, 3, 5
	v_lshlrev_b32_e32 v114, 4, v22
	v_mov_b32_e32 v115, v1
	v_mad_i64_i32 v[2:3], s[0:1], v6, s85, v[2:3]
	v_lshl_add_u64 v[116:117], v[4:5], 0, v[114:115]
	v_lshlrev_b32_e32 v0, 8, v126
	v_or_b32_e32 v23, 32, v126
	v_lshl_add_u64 v[18:19], v[2:3], 0, v[114:115]
	v_lshl_add_u64 v[2:3], v[116:117], 0, v[0:1]
	v_lshlrev_b32_e32 v0, 8, v23
	v_mad_u64_u32 v[6:7], s[0:1], v126, s85, v[18:19]
	v_lshl_add_u64 v[10:11], v[116:117], 0, v[0:1]
	v_mad_u64_u32 v[14:15], s[0:1], v23, s85, v[18:19]
	v_mov_b32 v122, 0xc2800000
	global_load_dwordx4 v[2:5], v[2:3], off
	s_nop 0
	global_load_dwordx4 v[6:9], v[6:7], off
	s_nop 0
	global_load_dwordx4 v[10:13], v[10:11], off
	s_nop 0
	global_load_dwordx4 v[14:17], v[14:15], off
	v_lshrrev_b32_e32 v26, 3, v20
	v_lshrrev_b32_e32 v25, 4, v20
	v_xor_b32_e32 v20, v26, v20
	v_lshlrev_b32_e32 v20, 4, v20
	v_and_b32_e32 v132, 0x70, v20
	v_lshlrev_b32_e32 v112, 3, v21
	v_lshlrev_b32_e32 v127, 7, v126
	v_bitop3_b32 v21, v21, v22, 4 bitop3:0x36
	v_add_u32_e32 v20, v150, v132
	v_and_b32_e32 v24, 64, v208
	v_mul_u32_u24_e32 v128, 0x90, v126
	v_lshlrev_b32_e32 v131, 7, v23
	v_lshlrev_b32_e32 v129, 4, v21
	v_add_u32_e32 v21, v20, v127
	v_xor_b32_e32 v0, 16, v208
	v_bitop3_b32 v25, v25, v22, 3 bitop3:0x6c
	v_add3_u32 v22, v150, v114, v128
	v_add_u32_e32 v20, v20, v131
	v_lshlrev_b32_e32 v130, 4, v25
	v_mov_b32_e32 v38, 0
	s_mov_b32 s0, 0
	v_lshlrev_b32_e32 v115, 7, v107
	v_mov_b32_e32 v123, v122
	v_mov_b32_e32 v165, 0
	v_mov_b32_e32 v152, 0x42800000
	v_mov_b32_e32 v153, v152
	v_mov_b32_e32 v154, v152
	v_mov_b32_e32 v155, v152
	v_mov_b32_e32 v156, v152
	v_mov_b32_e32 v157, v152
	v_mov_b32_e32 v158, v152
	v_mov_b32_e32 v159, v152
	v_mul_u32_u24_e32 v109, 0x90, v107
	v_mov_b32_e32 v39, v38
	v_mov_b32_e32 v40, v38
	v_mov_b32_e32 v41, v38
	v_mov_b32_e32 v34, v38
	v_mov_b32_e32 v35, v38
	v_mov_b32_e32 v36, v38
	v_mov_b32_e32 v37, v38
	s_waitcnt vmcnt(0) lgkmcnt(0)
	ds_write_b128 v21, v[2:5]
	ds_write_b128 v22, v[6:9] offset:8192
	ds_write_b128 v20, v[10:13]
	ds_write_b128 v22, v[14:17] offset:12800
	v_add_u32_e32 v2, 64, v24
	v_cmp_lt_i32_e32 vcc, v0, v2
	v_mov_b32_e32 v3, v1
	s_waitcnt lgkmcnt(0)
	v_cndmask_b32_e32 v0, v208, v0, vcc
	v_lshlrev_b32_e32 v111, 2, v0
	v_xor_b32_e32 v0, 32, v208
	v_cmp_lt_i32_e32 vcc, v0, v2
	v_mov_b32_e32 v2, v1
	s_barrier
	v_cndmask_b32_e32 v0, v208, v0, vcc
	v_lshlrev_b32_e32 v113, 2, v0
	v_mul_u32_u24_e32 v0, 0x1100, v126
	v_lshlrev_b32_e32 v0, 1, v0
	v_lshl_add_u64 v[120:121], v[18:19], 0, v[0:1]
	v_mov_b32_e32 v0, v1
	v_mov_b64_e32 v[20:21], v[2:3]
	v_mov_b64_e32 v[24:25], v[2:3]
	v_mov_b64_e32 v[28:29], v[2:3]
	v_mov_b64_e32 v[32:33], v[2:3]
	v_mov_b64_e32 v[12:13], v[2:3]
	v_mov_b64_e32 v[16:17], v[2:3]
	v_mov_b64_e32 v[8:9], v[2:3]
	v_mov_b64_e32 v[18:19], v[0:1]
	v_mov_b64_e32 v[22:23], v[0:1]
	v_mov_b64_e32 v[26:27], v[0:1]
	v_mov_b64_e32 v[30:31], v[0:1]
	v_mov_b64_e32 v[10:11], v[0:1]
	v_mov_b64_e32 v[14:15], v[0:1]
	v_mov_b64_e32 v[6:7], v[0:1]
	v_mov_b64_e32 v[4:5], v[2:3]
	v_mov_b64_e32 v[2:3], v[0:1]
	s_mov_b32 s1, 1
	v_lshl_or_b32 v68, s1, 6, v126
	v_lshlrev_b32_e32 v0, 8, v68
	s_lshl_b32 s56, s1, 7
	v_lshl_add_u64 v[58:59], v[116:117], 0, v[0:1]
	v_lshl_add_u64 v[66:67], v[120:121], 0, s[56:57]
	v_or_b32_e32 v0, 32, v68
	s_mov_b32 s1, 0x44000
	v_lshlrev_b64 v[68:69], 8, v[0:1]
	v_add_co_u32_e32 v70, vcc, s1, v66
	v_lshl_add_u64 v[68:69], v[116:117], 0, v[68:69]
	s_nop 0
	v_addc_co_u32_e32 v71, vcc, 0, v67, vcc
	global_load_dwordx4 v[58:61], v[58:59], off
	s_nop 0
	global_load_dwordx4 v[62:65], v[66:67], off
	s_nop 0
	global_load_dwordx4 v[66:69], v[68:69], off
	s_nop 0
	global_load_dwordx4 v[70:73], v[70:71], off
.LBB0_1275:
	s_bitcmp1_b32 s0, 0
	s_mov_b32 s1, s0
	s_cselect_b32 s2, 0x4400, 0
	s_add_i32 s0, s0, 1
	s_add_i32 s1, s0, 1
	s_min_u32 s1, s1, 0x43
	v_add_u32_e32 v0, s2, v150
	v_add_u32_e32 v86, v0, v115
	v_add_u32_e32 v102, v86, v130
	ds_read_b128 v[74:77], v102
	ds_read_b128 v[82:85], v102 offset:2048
	v_add_u32_e32 v103, v86, v129
	ds_read_b128 v[86:89], v103
	ds_read_b128 v[98:101], v103 offset:2048
	v_lshl_or_b32 v238, s1, 6, v126
	v_lshlrev_b32_e32 v164, 8, v238
	s_lshl_b32 s56, s1, 7
	v_lshl_add_u64 v[228:229], v[116:117], 0, v[164:165]
	v_lshl_add_u64 v[236:237], v[120:121], 0, s[56:57]
	v_or_b32_e32 v164, 32, v238
	s_mov_b32 s1, 0x44000
	v_lshlrev_b64 v[238:239], 8, v[164:165]
	v_add_co_u32_e32 v240, vcc, s1, v236
	v_lshl_add_u64 v[238:239], v[116:117], 0, v[238:239]
	s_nop 0
	v_addc_co_u32_e32 v241, vcc, 0, v237, vcc
	global_load_dwordx4 v[228:231], v[228:229], off
	s_nop 0
	global_load_dwordx4 v[232:235], v[236:237], off
	s_nop 0
	global_load_dwordx4 v[236:239], v[238:239], off
	s_nop 0
	global_load_dwordx4 v[240:243], v[240:241], off
	s_setprio 1
	s_waitcnt lgkmcnt(0)
	v_mfma_f32_16x16x32_bf16 v[78:81], v[74:77], v[46:49], v[152:155]
	v_mfma_f32_16x16x32_bf16 v[74:77], v[74:77], v[50:53], v[156:159]
	v_mfma_f32_16x16x32_bf16 v[94:97], v[86:89], v[42:45], v[78:81]
	v_mfma_f32_16x16x32_bf16 v[78:81], v[86:89], v[54:57], v[74:77]
	v_mfma_f32_16x16x32_bf16 v[74:77], v[82:85], v[46:49], v[152:155]
	v_mfma_f32_16x16x32_bf16 v[90:93], v[98:101], v[42:45], v[74:77]
	v_mfma_f32_16x16x32_bf16 v[74:77], v[82:85], v[50:53], v[156:159]
	ds_read_b128 v[82:85], v102 offset:4096
	ds_read_b128 v[134:137], v102 offset:6144
	v_mfma_f32_16x16x32_bf16 v[74:77], v[98:101], v[54:57], v[74:77]
	ds_read_b128 v[98:101], v103 offset:4096
	ds_read_b128 v[138:141], v103 offset:6144
	s_waitcnt lgkmcnt(0)
	v_add3_u32 v118, v0, v109, v112
	v_add_u32_e32 v119, 0x2000, v118
	v_add_u32_e32 v124, 0x2800, v118
	ds_read2_b64 v[212:215], v119 offset1:4
	ds_read2_b64 v[216:219], v119 offset0:8 offset1:12
	ds_read2_b64 v[244:247], v124 offset0:32 offset1:36
	ds_read2_b64 v[248:251], v124 offset0:40 offset1:44
	v_mfma_f32_16x16x32_bf16 v[86:89], v[82:85], v[46:49], v[152:155]
	v_mfma_f32_16x16x32_bf16 v[82:85], v[82:85], v[50:53], v[156:159]
	v_mfma_f32_16x16x32_bf16 v[102:105], v[98:101], v[42:45], v[86:89]
	v_mfma_f32_16x16x32_bf16 v[86:89], v[98:101], v[54:57], v[82:85]
	v_mfma_f32_16x16x32_bf16 v[82:85], v[134:137], v[46:49], v[152:155]
	v_mfma_f32_16x16x32_bf16 v[98:101], v[138:141], v[42:45], v[82:85]
	v_mfma_f32_16x16x32_bf16 v[82:85], v[134:137], v[50:53], v[156:159]
	v_mfma_f32_16x16x32_bf16 v[82:85], v[138:141], v[54:57], v[82:85]
	s_setprio 0
	v_max3_f32 v118, v94, v95, v96
	v_max3_f32 v119, v97, v90, v91
	v_max3_f32 v118, v118, v92, v93
	v_max3_f32 v118, v118, v119, v102
	v_max3_f32 v119, v103, v104, v105
	v_max3_f32 v118, v118, v119, v98
	v_max3_f32 v119, v99, v100, v101
	v_max_f32_e32 v118, v118, v119
	v_mov_b32_e32 v119, v118
	s_nop 1
	v_permlane16_swap_b32_e32 v119, v118
	v_max_f32_e32 v118, v118, v119
	v_mov_b32_e32 v119, v118
	s_nop 1
	v_permlane32_swap_b32_e32 v119, v118
	v_max_f32_e32 v118, v118, v119
	v_cmp_lt_f32_e32 vcc, 0x41000000, v118
	s_cbranch_vccz .LBB0_1277
	v_max_f32_e32 v119, 0, v118
	v_add_f32_e32 v124, v122, v119
	v_exp_f32_e64 v118, -v119
	v_mov_b32_e32 v125, v123
	v_mov_b32_e32 v122, v124
	v_xor_b32_e32 v152, 0x80000000, v124
	v_mov_b32_e32 v153, v152
	v_mov_b32_e32 v154, v152
	v_mov_b32_e32 v155, v152
	v_sub_f32_e32 v94, v94, v119
	v_sub_f32_e32 v95, v95, v119
	v_sub_f32_e32 v96, v96, v119
	v_sub_f32_e32 v97, v97, v119
	v_sub_f32_e32 v90, v90, v119
	v_sub_f32_e32 v91, v91, v119
	v_sub_f32_e32 v92, v92, v119
	v_sub_f32_e32 v93, v93, v119
	v_sub_f32_e32 v102, v102, v119
	v_sub_f32_e32 v103, v103, v119
	v_sub_f32_e32 v104, v104, v119
	v_sub_f32_e32 v105, v105, v119
	v_sub_f32_e32 v98, v98, v119
	v_sub_f32_e32 v99, v99, v119
	v_sub_f32_e32 v100, v100, v119
	v_sub_f32_e32 v101, v101, v119
	v_pk_mul_f32 v[38:39], v[38:39], v[118:119] op_sel_hi:[1,0]
	v_pk_mul_f32 v[40:41], v[40:41], v[118:119] op_sel_hi:[1,0]
	v_pk_mul_f32 v[32:33], v[32:33], v[118:119] op_sel_hi:[1,0]
	v_pk_mul_f32 v[30:31], v[30:31], v[118:119] op_sel_hi:[1,0]
	v_pk_mul_f32 v[24:25], v[24:25], v[118:119] op_sel_hi:[1,0]
	v_pk_mul_f32 v[22:23], v[22:23], v[118:119] op_sel_hi:[1,0]
	v_pk_mul_f32 v[12:13], v[12:13], v[118:119] op_sel_hi:[1,0]
	v_pk_mul_f32 v[10:11], v[10:11], v[118:119] op_sel_hi:[1,0]
	v_pk_mul_f32 v[8:9], v[8:9], v[118:119] op_sel_hi:[1,0]
	v_pk_mul_f32 v[6:7], v[6:7], v[118:119] op_sel_hi:[1,0]
	s_branch .LBB0_1278

.LBB0_1278:
	v_max3_f32 v118, v78, v79, v80
	v_max3_f32 v119, v81, v74, v75
	v_max3_f32 v118, v118, v76, v77
	v_max3_f32 v118, v118, v119, v86
	v_max3_f32 v119, v87, v88, v89
	v_max3_f32 v118, v118, v119, v82
	v_max3_f32 v119, v83, v84, v85
	v_max_f32_e32 v118, v118, v119
	v_mov_b32_e32 v119, v118
	s_nop 1
	v_permlane16_swap_b32_e32 v119, v118
	v_max_f32_e32 v118, v118, v119
	v_mov_b32_e32 v119, v118
	s_nop 1
	v_permlane32_swap_b32_e32 v119, v118
	v_max_f32_e32 v118, v118, v119
	v_cmp_lt_f32_e32 vcc, 0x41000000, v118
	s_cbranch_vccz .LBB0_1280
	v_max_f32_e32 v119, 0, v118
	v_add_f32_e32 v123, v125, v119
	v_exp_f32_e64 v118, -v119
	v_mov_b32_e32 v125, v123
	v_xor_b32_e32 v156, 0x80000000, v123
	v_mov_b32_e32 v157, v156
	v_mov_b32_e32 v158, v156
	v_mov_b32_e32 v159, v156
	v_sub_f32_e32 v78, v78, v119
	v_sub_f32_e32 v79, v79, v119
	v_sub_f32_e32 v80, v80, v119
	v_sub_f32_e32 v81, v81, v119
	v_sub_f32_e32 v74, v74, v119
	v_sub_f32_e32 v75, v75, v119
	v_sub_f32_e32 v76, v76, v119
	v_sub_f32_e32 v77, v77, v119
	v_sub_f32_e32 v86, v86, v119
	v_sub_f32_e32 v87, v87, v119
	v_sub_f32_e32 v88, v88, v119
	v_sub_f32_e32 v89, v89, v119
	v_sub_f32_e32 v82, v82, v119
	v_sub_f32_e32 v83, v83, v119
	v_sub_f32_e32 v84, v84, v119
	v_sub_f32_e32 v85, v85, v119
	v_pk_mul_f32 v[34:35], v[34:35], v[118:119] op_sel_hi:[1,0]
	v_pk_mul_f32 v[36:37], v[36:37], v[118:119] op_sel_hi:[1,0]
	v_pk_mul_f32 v[28:29], v[28:29], v[118:119] op_sel_hi:[1,0]
	v_pk_mul_f32 v[26:27], v[26:27], v[118:119] op_sel_hi:[1,0]
	v_pk_mul_f32 v[20:21], v[20:21], v[118:119] op_sel_hi:[1,0]
	v_pk_mul_f32 v[18:19], v[18:19], v[118:119] op_sel_hi:[1,0]
	v_pk_mul_f32 v[16:17], v[16:17], v[118:119] op_sel_hi:[1,0]
	v_pk_mul_f32 v[14:15], v[14:15], v[118:119] op_sel_hi:[1,0]
	v_pk_mul_f32 v[4:5], v[4:5], v[118:119] op_sel_hi:[1,0]
	v_pk_mul_f32 v[2:3], v[2:3], v[118:119] op_sel_hi:[1,0]
.LBB0_1280:
	v_exp_f32_e32 v134, v74
	v_exp_f32_e32 v135, v75
	v_exp_f32_e32 v136, v76
	v_exp_f32_e32 v137, v77
	v_exp_f32_e32 v138, v86
	v_exp_f32_e32 v139, v87
	v_exp_f32_e32 v140, v88
	v_exp_f32_e32 v141, v89
	v_exp_f32_e32 v122, v78
	v_exp_f32_e32 v142, v82
	v_exp_f32_e32 v123, v79
	v_exp_f32_e32 v143, v83
	s_mov_b32 s38, s36
	s_mov_b32 s39, s36
	v_mov_b64_e32 v[118:119], v[124:125]
	v_exp_f32_e32 v124, v80
	v_exp_f32_e32 v144, v84
	v_exp_f32_e32 v125, v85
	s_mov_b32 s37, s36
	v_mov_b64_e32 v[84:85], s[38:39]
	v_exp_f32_e32 v94, v94
	v_exp_f32_e32 v95, v95
	v_exp_f32_e32 v96, v96
	v_exp_f32_e32 v97, v97
	v_exp_f32_e32 v90, v90
	v_exp_f32_e32 v91, v91
	v_exp_f32_e32 v92, v92
	v_exp_f32_e32 v93, v93
	v_exp_f32_e32 v133, v81
	v_mov_b64_e32 v[82:83], s[36:37]
	v_exp_f32_e32 v102, v102
	v_exp_f32_e32 v103, v103
	v_exp_f32_e32 v104, v104
	v_exp_f32_e32 v105, v105
	v_exp_f32_e32 v98, v98
	v_exp_f32_e32 v99, v99
	v_exp_f32_e32 v100, v100
	v_exp_f32_e32 v101, v101
	v_cvt_pk_bf16_f32 v74, v94, v95
	v_cvt_pk_bf16_f32 v75, v96, v97
	v_cvt_pk_bf16_f32 v76, v90, v91
	v_cvt_pk_bf16_f32 v77, v92, v93
	v_cvt_pk_bf16_f32 v86, v122, v123
	v_cvt_pk_bf16_f32 v87, v124, v133
	v_cvt_pk_bf16_f32 v88, v134, v135
	v_cvt_pk_bf16_f32 v89, v136, v137
	v_mfma_f32_16x16x32_bf16 v[38:41], v[82:85], v[74:77], v[38:41]
	v_cvt_pk_bf16_f32 v78, v102, v103
	v_cvt_pk_bf16_f32 v79, v104, v105
	v_cvt_pk_bf16_f32 v80, v98, v99
	v_mfma_f32_16x16x32_bf16 v[34:37], v[82:85], v[86:89], v[34:37]
	v_cvt_pk_bf16_f32 v81, v100, v101
	v_cvt_pk_bf16_f32 v90, v138, v139
	v_cvt_pk_bf16_f32 v91, v140, v141
	v_cvt_pk_bf16_f32 v92, v142, v143
	v_cvt_pk_bf16_f32 v93, v144, v125
	v_mfma_f32_16x16x32_bf16 v[38:41], v[82:85], v[78:81], v[38:41]
	s_nop 0
	v_mfma_f32_16x16x32_bf16 v[34:37], v[82:85], v[90:93], v[34:37]
	s_setprio 1
	s_bitcmp1_b32 s0, 0
	s_cselect_b32 s1, 0x4400, 0
	v_add_u32_e32 v160, s1, v150
	v_add_u32_e32 v161, v160, v132
	v_add_u32_e32 v162, v161, v131
	v_add_u32_e32 v161, v161, v127
	v_add3_u32 v160, v160, v114, v128
	s_waitcnt vmcnt(4)
	ds_write_b128 v161, v[58:61]
	ds_write_b128 v160, v[62:65] offset:8192
	ds_write_b128 v162, v[66:69]
	ds_write_b128 v160, v[70:73] offset:12800
	v_add3_u32 v124, v0, v109, v112
	v_add_u32_e32 v125, 0x3000, v124
	v_add_u32_e32 v124, 0x3800, v124
	ds_read2_b64 v[94:97], v125 offset0:64 offset1:68
	ds_read2_b64 v[98:101], v125 offset0:72 offset1:76
	ds_read2_b64 v[102:105], v124 offset0:96 offset1:100
	ds_read2_b64 v[134:137], v124 offset0:104 offset1:108
	s_waitcnt lgkmcnt(4)
	v_mfma_f32_16x16x32_bf16 v[30:33], v[212:215], v[74:77], v[30:33]
	v_mfma_f32_16x16x32_bf16 v[26:29], v[212:215], v[86:89], v[26:29]
	v_mfma_f32_16x16x32_bf16 v[22:25], v[244:247], v[74:77], v[22:25]
	v_mfma_f32_16x16x32_bf16 v[18:21], v[244:247], v[86:89], v[18:21]
	v_mfma_f32_16x16x32_bf16 v[30:33], v[216:219], v[78:81], v[30:33]
	v_mfma_f32_16x16x32_bf16 v[26:29], v[216:219], v[90:93], v[26:29]
	v_mfma_f32_16x16x32_bf16 v[22:25], v[248:251], v[78:81], v[22:25]
	v_mfma_f32_16x16x32_bf16 v[18:21], v[248:251], v[90:93], v[18:21]
	s_waitcnt lgkmcnt(0)
	v_mfma_f32_16x16x32_bf16 v[10:13], v[94:97], v[74:77], v[10:13]
	v_mfma_f32_16x16x32_bf16 v[14:17], v[94:97], v[86:89], v[14:17]
	v_mfma_f32_16x16x32_bf16 v[6:9], v[102:105], v[74:77], v[6:9]
	v_mfma_f32_16x16x32_bf16 v[2:5], v[102:105], v[86:89], v[2:5]
	v_mfma_f32_16x16x32_bf16 v[10:13], v[98:101], v[78:81], v[10:13]
	v_mfma_f32_16x16x32_bf16 v[14:17], v[98:101], v[90:93], v[14:17]
	v_mfma_f32_16x16x32_bf16 v[6:9], v[134:137], v[78:81], v[6:9]
	v_mfma_f32_16x16x32_bf16 v[2:5], v[134:137], v[90:93], v[2:5]
	s_setprio 0
	s_cmpk_lg_i32 s0, 0x43
	s_waitcnt lgkmcnt(0)
	s_barrier
	s_cbranch_scc0 .LBB0_1282
	v_mov_b64_e32 v[122:123], v[118:119]
	s_branch .Lga_odd
.Lga_odd:
	s_bitcmp1_b32 s0, 0
	s_mov_b32 s1, s0
	s_cselect_b32 s2, 0x4400, 0
	s_add_i32 s0, s0, 1
	s_add_i32 s1, s0, 1
	s_min_u32 s1, s1, 0x43
	v_add_u32_e32 v0, s2, v150
	v_add_u32_e32 v86, v0, v115
	v_add_u32_e32 v102, v86, v130
	ds_read_b128 v[74:77], v102
	ds_read_b128 v[82:85], v102 offset:2048
	v_add_u32_e32 v103, v86, v129
	ds_read_b128 v[86:89], v103
	ds_read_b128 v[98:101], v103 offset:2048
	v_lshl_or_b32 v68, s1, 6, v126
	v_lshlrev_b32_e32 v164, 8, v68
	s_lshl_b32 s56, s1, 7
	v_lshl_add_u64 v[58:59], v[116:117], 0, v[164:165]
	v_lshl_add_u64 v[66:67], v[120:121], 0, s[56:57]
	v_or_b32_e32 v164, 32, v68
	s_mov_b32 s1, 0x44000
	v_lshlrev_b64 v[68:69], 8, v[164:165]
	v_add_co_u32_e32 v70, vcc, s1, v66
	v_lshl_add_u64 v[68:69], v[116:117], 0, v[68:69]
	s_nop 0
	v_addc_co_u32_e32 v71, vcc, 0, v67, vcc
	global_load_dwordx4 v[58:61], v[58:59], off
	s_nop 0
	global_load_dwordx4 v[62:65], v[66:67], off
	s_nop 0
	global_load_dwordx4 v[66:69], v[68:69], off
	s_nop 0
	global_load_dwordx4 v[70:73], v[70:71], off
	s_setprio 1
	s_waitcnt lgkmcnt(0)
	v_mfma_f32_16x16x32_bf16 v[78:81], v[74:77], v[46:49], v[152:155]
	v_mfma_f32_16x16x32_bf16 v[74:77], v[74:77], v[50:53], v[156:159]
	v_mfma_f32_16x16x32_bf16 v[94:97], v[86:89], v[42:45], v[78:81]
	v_mfma_f32_16x16x32_bf16 v[78:81], v[86:89], v[54:57], v[74:77]
	v_mfma_f32_16x16x32_bf16 v[74:77], v[82:85], v[46:49], v[152:155]
	v_mfma_f32_16x16x32_bf16 v[90:93], v[98:101], v[42:45], v[74:77]
	v_mfma_f32_16x16x32_bf16 v[74:77], v[82:85], v[50:53], v[156:159]
	ds_read_b128 v[82:85], v102 offset:4096
	ds_read_b128 v[134:137], v102 offset:6144
	v_mfma_f32_16x16x32_bf16 v[74:77], v[98:101], v[54:57], v[74:77]
	ds_read_b128 v[98:101], v103 offset:4096
	ds_read_b128 v[138:141], v103 offset:6144
	s_waitcnt lgkmcnt(0)
	v_add3_u32 v118, v0, v109, v112
	v_add_u32_e32 v119, 0x2000, v118
	v_add_u32_e32 v124, 0x2800, v118
	ds_read2_b64 v[212:215], v119 offset1:4
	ds_read2_b64 v[216:219], v119 offset0:8 offset1:12
	ds_read2_b64 v[244:247], v124 offset0:32 offset1:36
	ds_read2_b64 v[248:251], v124 offset0:40 offset1:44
	v_mfma_f32_16x16x32_bf16 v[86:89], v[82:85], v[46:49], v[152:155]
	v_mfma_f32_16x16x32_bf16 v[82:85], v[82:85], v[50:53], v[156:159]
	v_mfma_f32_16x16x32_bf16 v[102:105], v[98:101], v[42:45], v[86:89]
	v_mfma_f32_16x16x32_bf16 v[86:89], v[98:101], v[54:57], v[82:85]
	v_mfma_f32_16x16x32_bf16 v[82:85], v[134:137], v[46:49], v[152:155]
	v_mfma_f32_16x16x32_bf16 v[98:101], v[138:141], v[42:45], v[82:85]
	v_mfma_f32_16x16x32_bf16 v[82:85], v[134:137], v[50:53], v[156:159]
	v_mfma_f32_16x16x32_bf16 v[82:85], v[138:141], v[54:57], v[82:85]
	s_setprio 0
	v_max3_f32 v118, v94, v95, v96
	v_max3_f32 v119, v97, v90, v91
	v_max3_f32 v118, v118, v92, v93
	v_max3_f32 v118, v118, v119, v102
	v_max3_f32 v119, v103, v104, v105
	v_max3_f32 v118, v118, v119, v98
	v_max3_f32 v119, v99, v100, v101
	v_max_f32_e32 v118, v118, v119
	v_mov_b32_e32 v119, v118
	s_nop 1
	v_permlane16_swap_b32_e32 v119, v118
	v_max_f32_e32 v118, v118, v119
	v_mov_b32_e32 v119, v118
	s_nop 1
	v_permlane32_swap_b32_e32 v119, v118
	v_max_f32_e32 v118, v118, v119
	v_cmp_lt_f32_e32 vcc, 0x41000000, v118
	s_cbranch_vccz .Lga_o_1277
	v_max_f32_e32 v119, 0, v118
	v_add_f32_e32 v124, v122, v119
	v_exp_f32_e64 v118, -v119
	v_mov_b32_e32 v125, v123
	v_mov_b32_e32 v122, v124
	v_xor_b32_e32 v152, 0x80000000, v124
	v_mov_b32_e32 v153, v152
	v_mov_b32_e32 v154, v152
	v_mov_b32_e32 v155, v152
	v_sub_f32_e32 v94, v94, v119
	v_sub_f32_e32 v95, v95, v119
	v_sub_f32_e32 v96, v96, v119
	v_sub_f32_e32 v97, v97, v119
	v_sub_f32_e32 v90, v90, v119
	v_sub_f32_e32 v91, v91, v119
	v_sub_f32_e32 v92, v92, v119
	v_sub_f32_e32 v93, v93, v119
	v_sub_f32_e32 v102, v102, v119
	v_sub_f32_e32 v103, v103, v119
	v_sub_f32_e32 v104, v104, v119
	v_sub_f32_e32 v105, v105, v119
	v_sub_f32_e32 v98, v98, v119
	v_sub_f32_e32 v99, v99, v119
	v_sub_f32_e32 v100, v100, v119
	v_sub_f32_e32 v101, v101, v119
	v_pk_mul_f32 v[38:39], v[38:39], v[118:119] op_sel_hi:[1,0]
	v_pk_mul_f32 v[40:41], v[40:41], v[118:119] op_sel_hi:[1,0]
	v_pk_mul_f32 v[32:33], v[32:33], v[118:119] op_sel_hi:[1,0]
	v_pk_mul_f32 v[30:31], v[30:31], v[118:119] op_sel_hi:[1,0]
	v_pk_mul_f32 v[24:25], v[24:25], v[118:119] op_sel_hi:[1,0]
	v_pk_mul_f32 v[22:23], v[22:23], v[118:119] op_sel_hi:[1,0]
	v_pk_mul_f32 v[12:13], v[12:13], v[118:119] op_sel_hi:[1,0]
	v_pk_mul_f32 v[10:11], v[10:11], v[118:119] op_sel_hi:[1,0]
	v_pk_mul_f32 v[8:9], v[8:9], v[118:119] op_sel_hi:[1,0]
	v_pk_mul_f32 v[6:7], v[6:7], v[118:119] op_sel_hi:[1,0]
	s_branch .Lga_o_1278

.Lga_o_1280:
	v_exp_f32_e32 v134, v74
	v_exp_f32_e32 v135, v75
	v_exp_f32_e32 v136, v76
	v_exp_f32_e32 v137, v77
	v_exp_f32_e32 v138, v86
	v_exp_f32_e32 v139, v87
	v_exp_f32_e32 v140, v88
	v_exp_f32_e32 v141, v89
	v_exp_f32_e32 v122, v78
	v_exp_f32_e32 v142, v82
	v_exp_f32_e32 v123, v79
	v_exp_f32_e32 v143, v83
	s_mov_b32 s38, s36
	s_mov_b32 s39, s36
	v_mov_b64_e32 v[118:119], v[124:125]
	v_exp_f32_e32 v124, v80
	v_exp_f32_e32 v144, v84
	v_exp_f32_e32 v125, v85
	s_mov_b32 s37, s36
	v_mov_b64_e32 v[84:85], s[38:39]
	v_exp_f32_e32 v94, v94
	v_exp_f32_e32 v95, v95
	v_exp_f32_e32 v96, v96
	v_exp_f32_e32 v97, v97
	v_exp_f32_e32 v90, v90
	v_exp_f32_e32 v91, v91
	v_exp_f32_e32 v92, v92
	v_exp_f32_e32 v93, v93
	v_exp_f32_e32 v133, v81
	v_mov_b64_e32 v[82:83], s[36:37]
	v_exp_f32_e32 v102, v102
	v_exp_f32_e32 v103, v103
	v_exp_f32_e32 v104, v104
	v_exp_f32_e32 v105, v105
	v_exp_f32_e32 v98, v98
	v_exp_f32_e32 v99, v99
	v_exp_f32_e32 v100, v100
	v_exp_f32_e32 v101, v101
	v_cvt_pk_bf16_f32 v74, v94, v95
	v_cvt_pk_bf16_f32 v75, v96, v97
	v_cvt_pk_bf16_f32 v76, v90, v91
	v_cvt_pk_bf16_f32 v77, v92, v93
	v_cvt_pk_bf16_f32 v86, v122, v123
	v_cvt_pk_bf16_f32 v87, v124, v133
	v_cvt_pk_bf16_f32 v88, v134, v135
	v_cvt_pk_bf16_f32 v89, v136, v137
	v_mfma_f32_16x16x32_bf16 v[38:41], v[82:85], v[74:77], v[38:41]
	v_cvt_pk_bf16_f32 v78, v102, v103
	v_cvt_pk_bf16_f32 v79, v104, v105
	v_cvt_pk_bf16_f32 v80, v98, v99
	v_mfma_f32_16x16x32_bf16 v[34:37], v[82:85], v[86:89], v[34:37]
	v_cvt_pk_bf16_f32 v81, v100, v101
	v_cvt_pk_bf16_f32 v90, v138, v139
	v_cvt_pk_bf16_f32 v91, v140, v141
	v_cvt_pk_bf16_f32 v92, v142, v143
	v_cvt_pk_bf16_f32 v93, v144, v125
	v_mfma_f32_16x16x32_bf16 v[38:41], v[82:85], v[78:81], v[38:41]
	s_nop 0
	v_mfma_f32_16x16x32_bf16 v[34:37], v[82:85], v[90:93], v[34:37]
	s_setprio 1
	s_bitcmp1_b32 s0, 0
	s_cselect_b32 s1, 0x4400, 0
	v_add_u32_e32 v160, s1, v150
	v_add_u32_e32 v161, v160, v132
	v_add_u32_e32 v162, v161, v131
	v_add_u32_e32 v161, v161, v127
	v_add3_u32 v160, v160, v114, v128
	s_waitcnt vmcnt(4)
	ds_write_b128 v161, v[228:231]
	ds_write_b128 v160, v[232:235] offset:8192
	ds_write_b128 v162, v[236:239]
	ds_write_b128 v160, v[240:243] offset:12800
	v_add3_u32 v124, v0, v109, v112
	v_add_u32_e32 v125, 0x3000, v124
	v_add_u32_e32 v124, 0x3800, v124
	ds_read2_b64 v[94:97], v125 offset0:64 offset1:68
	ds_read2_b64 v[98:101], v125 offset0:72 offset1:76
	ds_read2_b64 v[102:105], v124 offset0:96 offset1:100
	ds_read2_b64 v[134:137], v124 offset0:104 offset1:108
	s_waitcnt lgkmcnt(4)
	v_mfma_f32_16x16x32_bf16 v[30:33], v[212:215], v[74:77], v[30:33]
	v_mfma_f32_16x16x32_bf16 v[26:29], v[212:215], v[86:89], v[26:29]
	v_mfma_f32_16x16x32_bf16 v[22:25], v[244:247], v[74:77], v[22:25]
	v_mfma_f32_16x16x32_bf16 v[18:21], v[244:247], v[86:89], v[18:21]
	v_mfma_f32_16x16x32_bf16 v[30:33], v[216:219], v[78:81], v[30:33]
	v_mfma_f32_16x16x32_bf16 v[26:29], v[216:219], v[90:93], v[26:29]
	v_mfma_f32_16x16x32_bf16 v[22:25], v[248:251], v[78:81], v[22:25]
	v_mfma_f32_16x16x32_bf16 v[18:21], v[248:251], v[90:93], v[18:21]
	s_waitcnt lgkmcnt(0)
	v_mfma_f32_16x16x32_bf16 v[10:13], v[94:97], v[74:77], v[10:13]
	v_mfma_f32_16x16x32_bf16 v[14:17], v[94:97], v[86:89], v[14:17]
	v_mfma_f32_16x16x32_bf16 v[6:9], v[102:105], v[74:77], v[6:9]
	v_mfma_f32_16x16x32_bf16 v[2:5], v[102:105], v[86:89], v[2:5]
	v_mfma_f32_16x16x32_bf16 v[10:13], v[98:101], v[78:81], v[10:13]
	v_mfma_f32_16x16x32_bf16 v[14:17], v[98:101], v[90:93], v[14:17]
	v_mfma_f32_16x16x32_bf16 v[6:9], v[134:137], v[78:81], v[6:9]
	v_mfma_f32_16x16x32_bf16 v[2:5], v[134:137], v[90:93], v[2:5]
	s_setprio 0
	s_cmpk_lg_i32 s0, 0x43
	s_waitcnt lgkmcnt(0)
	s_barrier
	s_cbranch_scc0 .LBB0_1282
	v_mov_b64_e32 v[122:123], v[118:119]
	s_branch .LBB0_1275
